# prep: workgroups 0..63 (S5 tables) skip the 4th weight-conversion iteration, 64..255 cover it with a virtual grid of 192; final RMSNorm phase with all row loads up front
# speedup vs baseline: 1.0228x; 1.0021x over previous
.LBB0_20:
	v_readlane_b32 s0, v254, 1
	v_readlane_b32 s33, v254, 0
	v_readlane_b32 s1, v254, 2
	s_load_dword s0, s[0:1], 0x10
	v_readlane_b32 s36, v254, 19
	s_mul_i32 s2, s8, 0x3000
	v_readlane_b32 s38, v254, 21
	v_readlane_b32 s39, v254, 22
	s_waitcnt lgkmcnt(0)
	s_lshr_b32 s0, s0, 16
	s_cmp_lg_u32 s0, 0
	s_cselect_b64 s[0:1], -1, 0
	s_cmp_lg_u64 s[0:1], 0
	s_addc_u32 s18, s69, 0
	s_lshl_b32 s26, s8, 1
	s_add_u32 s70, s38, s2
	s_addc_u32 s71, s39, 0
	s_mul_i32 s0, s8, 0x2100000
	v_readlane_b32 s2, v254, 40
	s_mul_hi_u32 s1, s26, 0x1080000
	v_readlane_b32 s3, v254, 41
	s_add_u32 s0, s2, s0
	s_addc_u32 s1, s3, s1
	s_mov_b32 s27, s18
	s_cmp_eq_u32 s18, 0x100
	s_cbranch_scc0 .Lw_norm
	s_cmp_eq_u32 s8, 3
	s_cbranch_scc0 .Lw_norm
	s_cmp_lt_u32 s33, 64
	s_cbranch_scc1 .LBB0_19
	s_sub_i32 s33, s33, 64
	s_movk_i32 s27, 0xc0
.Lw_norm:
	s_cmpk_lt_i32 s33, 0x2c0
	s_mul_i32 s24, s8, 0x580000
	s_mul_hi_u32 s25, s26, 0x2c0000
	v_mov_b32_e32 v0, v173
	s_cselect_b64 s[68:69], -1, 0
	s_cmpk_gt_i32 s33, 0x2bf
	v_readlane_b32 s37, v254, 20
	v_readlane_b32 s40, v254, 23
	v_readlane_b32 s41, v254, 24
	v_readlane_b32 s42, v254, 25
	v_readlane_b32 s43, v254, 26
	s_cbranch_scc1 .LBB0_101
	v_ashrrev_i32_e32 v87, 4, v0
	v_lshlrev_b32_e32 v0, 2, v0
	v_and_b32_e32 v88, 60, v0
	v_readlane_b32 s36, v254, 19
	s_lshl_b64 s[2:3], s[24:25], 2
	v_readlane_b32 s40, v254, 23
	v_lshlrev_b32_e32 v64, 2, v88
	v_readlane_b32 s41, v254, 24
	s_add_u32 s2, s40, s2
	v_add_u32_e32 v89, 0, v64
	s_addc_u32 s3, s41, s3
	v_mul_lo_u32 v90, v87, s66
	v_add_u32_e32 v0, 0x10400, v89
	v_add_u32_e32 v1, 0x14500, v89
	v_add_u32_e32 v2, 0x18600, v89
	v_add_u32_e32 v3, 0x1c700, v89
	s_lshl_b32 s10, s27, 3
	v_lshl_add_u64 v[66:67], s[2:3], 0, v[64:65]
	s_lshl_b32 s11, s33, 6
	s_lshl_b32 s12, s27, 9
	v_add_u32_e32 v91, v0, v90
	v_add_u32_e32 v92, v1, v90
	v_add_u32_e32 v93, v2, v90
	v_add_u32_e32 v94, v3, v90
	s_mov_b32 s13, s33
	v_readlane_b32 s37, v254, 20
	v_readlane_b32 s38, v254, 21
	v_readlane_b32 s39, v254, 22
	v_readlane_b32 s42, v254, 25
	v_readlane_b32 s43, v254, 26
	s_branch .LBB0_23

.LBB0_401:
	s_or_b32 s26, s26, 1
	s_add_u32 s24, s70, 0x2000
	s_addc_u32 s25, s71, 0
	s_mul_i32 s0, s26, 0x1080000
	v_readlane_b32 s2, v254, 40
	s_mul_hi_u32 s1, s26, 0x1080000
	v_readlane_b32 s3, v254, 41
	s_add_u32 s0, s2, s0
	v_readlane_b32 s12, v254, 0
	s_addc_u32 s1, s3, s1
	s_mov_b32 s13, s18
	s_cmp_eq_u32 s18, 0x100
	s_cbranch_scc0 .Lw_norm2
	s_cmp_eq_u32 s8, 3
	s_cbranch_scc0 .Lw_norm2
	s_sub_i32 s12, s12, 64
	s_movk_i32 s13, 0xc0
.Lw_norm2:
	s_cmpk_lt_i32 s12, 0x2c0
	s_mul_hi_u32 s71, s26, 0x2c0000
	s_mul_i32 s70, s26, 0x2c0000
	v_mov_b32_e32 v0, v173
	s_cselect_b64 s[74:75], -1, 0
	s_cmpk_gt_i32 s12, 0x2bf
	s_cbranch_scc1 .LBB0_482
	v_ashrrev_i32_e32 v87, 4, v0
	v_lshlrev_b32_e32 v0, 2, v0
	v_and_b32_e32 v88, 60, v0
	v_readlane_b32 s36, v254, 19
	s_lshl_b64 s[2:3], s[70:71], 2
	v_readlane_b32 s40, v254, 23
	v_lshlrev_b32_e32 v64, 2, v88
	v_readlane_b32 s41, v254, 24
	s_add_u32 s2, s40, s2
	v_add_u32_e32 v89, 0, v64
	v_readlane_b32 s37, v254, 20
	s_addc_u32 s3, s41, s3
	v_mul_lo_u32 v90, v87, s66
	v_add_u32_e32 v0, 0x10400, v89
	v_add_u32_e32 v1, 0x14500, v89
	v_add_u32_e32 v2, 0x18600, v89
	v_add_u32_e32 v3, 0x1c700, v89
	s_lshl_b32 s27, s13, 3
	v_lshl_add_u64 v[66:67], s[2:3], 0, v[64:65]
	s_lshl_b32 s33, s12, 6
	s_lshl_b32 s36, s13, 9
	v_add_u32_e32 v91, v0, v90
	v_add_u32_e32 v92, v1, v90
	v_add_u32_e32 v93, v2, v90
	v_add_u32_e32 v94, v3, v90
	s_mov_b32 s37, s12
	v_readlane_b32 s38, v254, 21
	v_readlane_b32 s39, v254, 22
	v_readlane_b32 s42, v254, 25
	v_readlane_b32 s43, v254, 26
	s_branch .LBB0_404

.LBB0_1712:
	s_cmp_lt_i32 s62, 34
	s_cselect_b64 s[0:1], -1, 0
	s_cmp_gt_i32 s63, 33
	s_cselect_b64 s[2:3], -1, 0
	s_and_b64 s[0:1], s[0:1], s[2:3]
	s_and_b64 vcc, exec, s[0:1]
	s_cbranch_vccz .LBB0_1770
	s_mov_b32 s0, s69
	s_load_dwordx4 s[4:7], s[66:67], 0xd0
	v_readlane_b32 s1, v254, 0
	s_mov_b32 s0, s1
	v_mov_b32_e32 v1, v173
	s_movk_i32 s0, 0x4000
	v_ashrrev_i32_e32 v0, 6, v1
	v_lshl_add_u32 v0, s1, 3, v0
	v_cmp_gt_i32_e32 vcc, s0, v0
	s_and_saveexec_b64 s[0:1], vcc
	s_cbranch_execz .LBB0_1716
	s_cmp_eq_u32 s69, 0x100
	s_cbranch_scc0 .Lfin_orig
	s_load_dwordx2 s[10:11], s[66:67], 0x28
	v_lshlrev_b32_e32 v1, 3, v173
	v_and_b32_e32 v2, 0x1f8, v1
	v_mov_b32_e32 v1, 0
	v_mov_b32_e32 v3, 0
	s_waitcnt lgkmcnt(0)
	s_add_u32 s2, s6, 0xd400000
	s_addc_u32 s3, s7, 0
	s_add_u32 s8, s6, 0xb400000
	s_addc_u32 s9, s7, 0
	v_lshlrev_b32_e32 v4, 2, v2
	v_mov_b32_e32 v5, 0
	v_lshl_add_u64 v[4:5], s[10:11], 0, v[4:5]
	global_load_dwordx4 v[16:19], v[4:5], off
	global_load_dwordx4 v[20:23], v[4:5], off offset:16
	global_load_dwordx4 v[24:27], v[4:5], off offset:2048
	global_load_dwordx4 v[28:31], v[4:5], off offset:2064
	v_lshlrev_b64 v[248:249], 6, v[0:1]
	v_lshl_add_u64 v[248:249], s[2:3], 0, v[248:249]
	v_lshlrev_b64 v[6:7], 10, v[0:1]
	v_or_b32_e32 v6, v6, v2
	v_lshl_add_u64 v[250:251], v[6:7], 1, s[8:9]
	v_lshl_add_u64 v[252:253], v[6:7], 2, s[4:5]
	s_mov_b64 s[12:13], 0x20000
	s_mov_b64 s[14:15], 0x400000
	s_mov_b64 s[16:17], 0x800000
	global_load_dwordx4 v[32:35], v[248:249], off
	global_load_dwordx4 v[36:39], v[248:249], off offset:16
	global_load_dwordx4 v[40:43], v[248:249], off offset:32
	global_load_dwordx4 v[44:47], v[248:249], off offset:48
	global_load_dwordx4 v[48:51], v[250:251], off
	global_load_dwordx4 v[52:55], v[250:251], off offset:1024
	v_lshl_add_u64 v[248:249], v[248:249], 0, s[12:13]
	v_lshl_add_u64 v[250:251], v[250:251], 0, s[14:15]
	global_load_dwordx4 v[56:59], v[248:249], off
	global_load_dwordx4 v[60:63], v[248:249], off offset:16
	global_load_dwordx4 v[64:67], v[248:249], off offset:32
	global_load_dwordx4 v[68:71], v[248:249], off offset:48
	global_load_dwordx4 v[72:75], v[250:251], off
	global_load_dwordx4 v[76:79], v[250:251], off offset:1024
	v_lshl_add_u64 v[248:249], v[248:249], 0, s[12:13]
	v_lshl_add_u64 v[250:251], v[250:251], 0, s[14:15]
	global_load_dwordx4 v[80:83], v[248:249], off
	global_load_dwordx4 v[84:87], v[248:249], off offset:16
	global_load_dwordx4 v[88:91], v[248:249], off offset:32
	global_load_dwordx4 v[92:95], v[248:249], off offset:48
	global_load_dwordx4 v[96:99], v[250:251], off
	global_load_dwordx4 v[100:103], v[250:251], off offset:1024
	v_lshl_add_u64 v[248:249], v[248:249], 0, s[12:13]
	v_lshl_add_u64 v[250:251], v[250:251], 0, s[14:15]
	global_load_dwordx4 v[104:107], v[248:249], off
	global_load_dwordx4 v[108:111], v[248:249], off offset:16
	global_load_dwordx4 v[112:115], v[248:249], off offset:32
	global_load_dwordx4 v[116:119], v[248:249], off offset:48
	global_load_dwordx4 v[120:123], v[250:251], off
	global_load_dwordx4 v[124:127], v[250:251], off offset:1024
	v_lshl_add_u64 v[248:249], v[248:249], 0, s[12:13]
	v_lshl_add_u64 v[250:251], v[250:251], 0, s[14:15]
	global_load_dwordx4 v[128:131], v[248:249], off
	global_load_dwordx4 v[132:135], v[248:249], off offset:16
	global_load_dwordx4 v[136:139], v[248:249], off offset:32
	global_load_dwordx4 v[140:143], v[248:249], off offset:48
	global_load_dwordx4 v[144:147], v[250:251], off
	global_load_dwordx4 v[148:151], v[250:251], off offset:1024
	v_lshl_add_u64 v[248:249], v[248:249], 0, s[12:13]
	v_lshl_add_u64 v[250:251], v[250:251], 0, s[14:15]
	global_load_dwordx4 v[176:179], v[248:249], off
	global_load_dwordx4 v[180:183], v[248:249], off offset:16
	global_load_dwordx4 v[184:187], v[248:249], off offset:32
	global_load_dwordx4 v[188:191], v[248:249], off offset:48
	global_load_dwordx4 v[192:195], v[250:251], off
	global_load_dwordx4 v[196:199], v[250:251], off offset:1024
	v_lshl_add_u64 v[248:249], v[248:249], 0, s[12:13]
	v_lshl_add_u64 v[250:251], v[250:251], 0, s[14:15]
	global_load_dwordx4 v[200:203], v[248:249], off
	global_load_dwordx4 v[204:207], v[248:249], off offset:16
	global_load_dwordx4 v[208:211], v[248:249], off offset:32
	global_load_dwordx4 v[212:215], v[248:249], off offset:48
	global_load_dwordx4 v[216:219], v[250:251], off
	global_load_dwordx4 v[220:223], v[250:251], off offset:1024
	v_lshl_add_u64 v[248:249], v[248:249], 0, s[12:13]
	v_lshl_add_u64 v[250:251], v[250:251], 0, s[14:15]
	global_load_dwordx4 v[224:227], v[248:249], off
	global_load_dwordx4 v[228:231], v[248:249], off offset:16
	global_load_dwordx4 v[232:235], v[248:249], off offset:32
	global_load_dwordx4 v[236:239], v[248:249], off offset:48
	global_load_dwordx4 v[240:243], v[250:251], off
	global_load_dwordx4 v[244:247], v[250:251], off offset:1024
	s_waitcnt vmcnt(42)
	v_add_f32_e32 v4, v32, v33
	v_add_f32_e32 v5, v34, v35
	v_add_f32_e32 v4, v4, v5
	v_add_f32_e32 v5, v36, v37
	v_add_f32_e32 v6, v38, v39
	v_add_f32_e32 v5, v5, v6
	v_add_f32_e32 v4, v4, v5
	v_add_f32_e32 v5, v40, v41
	v_add_f32_e32 v6, v42, v43
	v_add_f32_e32 v5, v5, v6
	v_add_f32_e32 v4, v4, v5
	v_add_f32_e32 v5, v44, v45
	v_add_f32_e32 v6, v46, v47
	v_add_f32_e32 v5, v5, v6
	v_add_f32_e32 v4, v4, v5
	v_mov_b32_e32 v5, 0x358637bd
	v_fmamk_f32 v4, v4, 0x3a800000, v5
	v_rsq_f32_e32 v14, v4
	v_lshlrev_b32_e32 v32, 16, v48
	v_and_b32_e32 v33, 0xffff0000, v48
	v_lshlrev_b32_e32 v34, 16, v49
	v_and_b32_e32 v35, 0xffff0000, v49
	v_lshlrev_b32_e32 v36, 16, v50
	v_and_b32_e32 v37, 0xffff0000, v50
	v_lshlrev_b32_e32 v38, 16, v51
	v_and_b32_e32 v39, 0xffff0000, v51
	v_lshlrev_b32_e32 v40, 16, v52
	v_and_b32_e32 v41, 0xffff0000, v52
	v_lshlrev_b32_e32 v42, 16, v53
	v_and_b32_e32 v43, 0xffff0000, v53
	v_lshlrev_b32_e32 v44, 16, v54
	v_and_b32_e32 v45, 0xffff0000, v54
	v_lshlrev_b32_e32 v46, 16, v55
	v_and_b32_e32 v47, 0xffff0000, v55
	v_pk_mul_f32 v[32:33], v[14:15], v[32:33] op_sel_hi:[0,1]
	v_pk_mul_f32 v[34:35], v[14:15], v[34:35] op_sel_hi:[0,1]
	v_pk_mul_f32 v[36:37], v[14:15], v[36:37] op_sel_hi:[0,1]
	v_pk_mul_f32 v[38:39], v[14:15], v[38:39] op_sel_hi:[0,1]
	v_pk_mul_f32 v[40:41], v[14:15], v[40:41] op_sel_hi:[0,1]
	v_pk_mul_f32 v[42:43], v[14:15], v[42:43] op_sel_hi:[0,1]
	v_pk_mul_f32 v[44:45], v[14:15], v[44:45] op_sel_hi:[0,1]
	v_pk_mul_f32 v[46:47], v[14:15], v[46:47] op_sel_hi:[0,1]
	v_pk_mul_f32 v[32:33], v[16:17], v[32:33]
	v_pk_mul_f32 v[34:35], v[18:19], v[34:35]
	v_pk_mul_f32 v[36:37], v[20:21], v[36:37]
	v_pk_mul_f32 v[38:39], v[22:23], v[38:39]
	v_pk_mul_f32 v[40:41], v[24:25], v[40:41]
	v_pk_mul_f32 v[42:43], v[26:27], v[42:43]
	v_pk_mul_f32 v[44:45], v[28:29], v[44:45]
	v_pk_mul_f32 v[46:47], v[30:31], v[46:47]
	global_store_dwordx4 v[252:253], v[32:35], off
	global_store_dwordx4 v[252:253], v[36:39], off offset:16
	global_store_dwordx4 v[252:253], v[40:43], off offset:2048
	global_store_dwordx4 v[252:253], v[44:47], off offset:2064
	v_lshl_add_u64 v[252:253], v[252:253], 0, s[16:17]
	s_waitcnt vmcnt(40)
	v_add_f32_e32 v4, v56, v57
	v_add_f32_e32 v5, v58, v59
	v_add_f32_e32 v4, v4, v5
	v_add_f32_e32 v5, v60, v61
	v_add_f32_e32 v6, v62, v63
	v_add_f32_e32 v5, v5, v6
	v_add_f32_e32 v4, v4, v5
	v_add_f32_e32 v5, v64, v65
	v_add_f32_e32 v6, v66, v67
	v_add_f32_e32 v5, v5, v6
	v_add_f32_e32 v4, v4, v5
	v_add_f32_e32 v5, v68, v69
	v_add_f32_e32 v6, v70, v71
	v_add_f32_e32 v5, v5, v6
	v_add_f32_e32 v4, v4, v5
	v_mov_b32_e32 v5, 0x358637bd
	v_fmamk_f32 v4, v4, 0x3a800000, v5
	v_rsq_f32_e32 v14, v4
	v_lshlrev_b32_e32 v56, 16, v72
	v_and_b32_e32 v57, 0xffff0000, v72
	v_lshlrev_b32_e32 v58, 16, v73
	v_and_b32_e32 v59, 0xffff0000, v73
	v_lshlrev_b32_e32 v60, 16, v74
	v_and_b32_e32 v61, 0xffff0000, v74
	v_lshlrev_b32_e32 v62, 16, v75
	v_and_b32_e32 v63, 0xffff0000, v75
	v_lshlrev_b32_e32 v64, 16, v76
	v_and_b32_e32 v65, 0xffff0000, v76
	v_lshlrev_b32_e32 v66, 16, v77
	v_and_b32_e32 v67, 0xffff0000, v77
	v_lshlrev_b32_e32 v68, 16, v78
	v_and_b32_e32 v69, 0xffff0000, v78
	v_lshlrev_b32_e32 v70, 16, v79
	v_and_b32_e32 v71, 0xffff0000, v79
	v_pk_mul_f32 v[56:57], v[14:15], v[56:57] op_sel_hi:[0,1]
	v_pk_mul_f32 v[58:59], v[14:15], v[58:59] op_sel_hi:[0,1]
	v_pk_mul_f32 v[60:61], v[14:15], v[60:61] op_sel_hi:[0,1]
	v_pk_mul_f32 v[62:63], v[14:15], v[62:63] op_sel_hi:[0,1]
	v_pk_mul_f32 v[64:65], v[14:15], v[64:65] op_sel_hi:[0,1]
	v_pk_mul_f32 v[66:67], v[14:15], v[66:67] op_sel_hi:[0,1]
	v_pk_mul_f32 v[68:69], v[14:15], v[68:69] op_sel_hi:[0,1]
	v_pk_mul_f32 v[70:71], v[14:15], v[70:71] op_sel_hi:[0,1]
	v_pk_mul_f32 v[56:57], v[16:17], v[56:57]
	v_pk_mul_f32 v[58:59], v[18:19], v[58:59]
	v_pk_mul_f32 v[60:61], v[20:21], v[60:61]
	v_pk_mul_f32 v[62:63], v[22:23], v[62:63]
	v_pk_mul_f32 v[64:65], v[24:25], v[64:65]
	v_pk_mul_f32 v[66:67], v[26:27], v[66:67]
	v_pk_mul_f32 v[68:69], v[28:29], v[68:69]
	v_pk_mul_f32 v[70:71], v[30:31], v[70:71]
	global_store_dwordx4 v[252:253], v[56:59], off
	global_store_dwordx4 v[252:253], v[60:63], off offset:16
	global_store_dwordx4 v[252:253], v[64:67], off offset:2048
	global_store_dwordx4 v[252:253], v[68:71], off offset:2064
	v_lshl_add_u64 v[252:253], v[252:253], 0, s[16:17]
	s_waitcnt vmcnt(38)
	v_add_f32_e32 v4, v80, v81
	v_add_f32_e32 v5, v82, v83
	v_add_f32_e32 v4, v4, v5
	v_add_f32_e32 v5, v84, v85
	v_add_f32_e32 v6, v86, v87
	v_add_f32_e32 v5, v5, v6
	v_add_f32_e32 v4, v4, v5
	v_add_f32_e32 v5, v88, v89
	v_add_f32_e32 v6, v90, v91
	v_add_f32_e32 v5, v5, v6
	v_add_f32_e32 v4, v4, v5
	v_add_f32_e32 v5, v92, v93
	v_add_f32_e32 v6, v94, v95
	v_add_f32_e32 v5, v5, v6
	v_add_f32_e32 v4, v4, v5
	v_mov_b32_e32 v5, 0x358637bd
	v_fmamk_f32 v4, v4, 0x3a800000, v5
	v_rsq_f32_e32 v14, v4
	v_lshlrev_b32_e32 v80, 16, v96
	v_and_b32_e32 v81, 0xffff0000, v96
	v_lshlrev_b32_e32 v82, 16, v97
	v_and_b32_e32 v83, 0xffff0000, v97
	v_lshlrev_b32_e32 v84, 16, v98
	v_and_b32_e32 v85, 0xffff0000, v98
	v_lshlrev_b32_e32 v86, 16, v99
	v_and_b32_e32 v87, 0xffff0000, v99
	v_lshlrev_b32_e32 v88, 16, v100
	v_and_b32_e32 v89, 0xffff0000, v100
	v_lshlrev_b32_e32 v90, 16, v101
	v_and_b32_e32 v91, 0xffff0000, v101
	v_lshlrev_b32_e32 v92, 16, v102
	v_and_b32_e32 v93, 0xffff0000, v102
	v_lshlrev_b32_e32 v94, 16, v103
	v_and_b32_e32 v95, 0xffff0000, v103
	v_pk_mul_f32 v[80:81], v[14:15], v[80:81] op_sel_hi:[0,1]
	v_pk_mul_f32 v[82:83], v[14:15], v[82:83] op_sel_hi:[0,1]
	v_pk_mul_f32 v[84:85], v[14:15], v[84:85] op_sel_hi:[0,1]
	v_pk_mul_f32 v[86:87], v[14:15], v[86:87] op_sel_hi:[0,1]
	v_pk_mul_f32 v[88:89], v[14:15], v[88:89] op_sel_hi:[0,1]
	v_pk_mul_f32 v[90:91], v[14:15], v[90:91] op_sel_hi:[0,1]
	v_pk_mul_f32 v[92:93], v[14:15], v[92:93] op_sel_hi:[0,1]
	v_pk_mul_f32 v[94:95], v[14:15], v[94:95] op_sel_hi:[0,1]
	v_pk_mul_f32 v[80:81], v[16:17], v[80:81]
	v_pk_mul_f32 v[82:83], v[18:19], v[82:83]
	v_pk_mul_f32 v[84:85], v[20:21], v[84:85]
	v_pk_mul_f32 v[86:87], v[22:23], v[86:87]
	v_pk_mul_f32 v[88:89], v[24:25], v[88:89]
	v_pk_mul_f32 v[90:91], v[26:27], v[90:91]
	v_pk_mul_f32 v[92:93], v[28:29], v[92:93]
	v_pk_mul_f32 v[94:95], v[30:31], v[94:95]
	global_store_dwordx4 v[252:253], v[80:83], off
	global_store_dwordx4 v[252:253], v[84:87], off offset:16
	global_store_dwordx4 v[252:253], v[88:91], off offset:2048
	global_store_dwordx4 v[252:253], v[92:95], off offset:2064
	v_lshl_add_u64 v[252:253], v[252:253], 0, s[16:17]
	s_waitcnt vmcnt(36)
	v_add_f32_e32 v4, v104, v105
	v_add_f32_e32 v5, v106, v107
	v_add_f32_e32 v4, v4, v5
	v_add_f32_e32 v5, v108, v109
	v_add_f32_e32 v6, v110, v111
	v_add_f32_e32 v5, v5, v6
	v_add_f32_e32 v4, v4, v5
	v_add_f32_e32 v5, v112, v113
	v_add_f32_e32 v6, v114, v115
	v_add_f32_e32 v5, v5, v6
	v_add_f32_e32 v4, v4, v5
	v_add_f32_e32 v5, v116, v117
	v_add_f32_e32 v6, v118, v119
	v_add_f32_e32 v5, v5, v6
	v_add_f32_e32 v4, v4, v5
	v_mov_b32_e32 v5, 0x358637bd
	v_fmamk_f32 v4, v4, 0x3a800000, v5
	v_rsq_f32_e32 v14, v4
	v_lshlrev_b32_e32 v104, 16, v120
	v_and_b32_e32 v105, 0xffff0000, v120
	v_lshlrev_b32_e32 v106, 16, v121
	v_and_b32_e32 v107, 0xffff0000, v121
	v_lshlrev_b32_e32 v108, 16, v122
	v_and_b32_e32 v109, 0xffff0000, v122
	v_lshlrev_b32_e32 v110, 16, v123
	v_and_b32_e32 v111, 0xffff0000, v123
	v_lshlrev_b32_e32 v112, 16, v124
	v_and_b32_e32 v113, 0xffff0000, v124
	v_lshlrev_b32_e32 v114, 16, v125
	v_and_b32_e32 v115, 0xffff0000, v125
	v_lshlrev_b32_e32 v116, 16, v126
	v_and_b32_e32 v117, 0xffff0000, v126
	v_lshlrev_b32_e32 v118, 16, v127
	v_and_b32_e32 v119, 0xffff0000, v127
	v_pk_mul_f32 v[104:105], v[14:15], v[104:105] op_sel_hi:[0,1]
	v_pk_mul_f32 v[106:107], v[14:15], v[106:107] op_sel_hi:[0,1]
	v_pk_mul_f32 v[108:109], v[14:15], v[108:109] op_sel_hi:[0,1]
	v_pk_mul_f32 v[110:111], v[14:15], v[110:111] op_sel_hi:[0,1]
	v_pk_mul_f32 v[112:113], v[14:15], v[112:113] op_sel_hi:[0,1]
	v_pk_mul_f32 v[114:115], v[14:15], v[114:115] op_sel_hi:[0,1]
	v_pk_mul_f32 v[116:117], v[14:15], v[116:117] op_sel_hi:[0,1]
	v_pk_mul_f32 v[118:119], v[14:15], v[118:119] op_sel_hi:[0,1]
	v_pk_mul_f32 v[104:105], v[16:17], v[104:105]
	v_pk_mul_f32 v[106:107], v[18:19], v[106:107]
	v_pk_mul_f32 v[108:109], v[20:21], v[108:109]
	v_pk_mul_f32 v[110:111], v[22:23], v[110:111]
	v_pk_mul_f32 v[112:113], v[24:25], v[112:113]
	v_pk_mul_f32 v[114:115], v[26:27], v[114:115]
	v_pk_mul_f32 v[116:117], v[28:29], v[116:117]
	v_pk_mul_f32 v[118:119], v[30:31], v[118:119]
	global_store_dwordx4 v[252:253], v[104:107], off
	global_store_dwordx4 v[252:253], v[108:111], off offset:16
	global_store_dwordx4 v[252:253], v[112:115], off offset:2048
	global_store_dwordx4 v[252:253], v[116:119], off offset:2064
	v_lshl_add_u64 v[252:253], v[252:253], 0, s[16:17]
	s_waitcnt vmcnt(34)
	v_add_f32_e32 v4, v128, v129
	v_add_f32_e32 v5, v130, v131
	v_add_f32_e32 v4, v4, v5
	v_add_f32_e32 v5, v132, v133
	v_add_f32_e32 v6, v134, v135
	v_add_f32_e32 v5, v5, v6
	v_add_f32_e32 v4, v4, v5
	v_add_f32_e32 v5, v136, v137
	v_add_f32_e32 v6, v138, v139
	v_add_f32_e32 v5, v5, v6
	v_add_f32_e32 v4, v4, v5
	v_add_f32_e32 v5, v140, v141
	v_add_f32_e32 v6, v142, v143
	v_add_f32_e32 v5, v5, v6
	v_add_f32_e32 v4, v4, v5
	v_mov_b32_e32 v5, 0x358637bd
	v_fmamk_f32 v4, v4, 0x3a800000, v5
	v_rsq_f32_e32 v14, v4
	v_lshlrev_b32_e32 v128, 16, v144
	v_and_b32_e32 v129, 0xffff0000, v144
	v_lshlrev_b32_e32 v130, 16, v145
	v_and_b32_e32 v131, 0xffff0000, v145
	v_lshlrev_b32_e32 v132, 16, v146
	v_and_b32_e32 v133, 0xffff0000, v146
	v_lshlrev_b32_e32 v134, 16, v147
	v_and_b32_e32 v135, 0xffff0000, v147
	v_lshlrev_b32_e32 v136, 16, v148
	v_and_b32_e32 v137, 0xffff0000, v148
	v_lshlrev_b32_e32 v138, 16, v149
	v_and_b32_e32 v139, 0xffff0000, v149
	v_lshlrev_b32_e32 v140, 16, v150
	v_and_b32_e32 v141, 0xffff0000, v150
	v_lshlrev_b32_e32 v142, 16, v151
	v_and_b32_e32 v143, 0xffff0000, v151
	v_pk_mul_f32 v[128:129], v[14:15], v[128:129] op_sel_hi:[0,1]
	v_pk_mul_f32 v[130:131], v[14:15], v[130:131] op_sel_hi:[0,1]
	v_pk_mul_f32 v[132:133], v[14:15], v[132:133] op_sel_hi:[0,1]
	v_pk_mul_f32 v[134:135], v[14:15], v[134:135] op_sel_hi:[0,1]
	v_pk_mul_f32 v[136:137], v[14:15], v[136:137] op_sel_hi:[0,1]
	v_pk_mul_f32 v[138:139], v[14:15], v[138:139] op_sel_hi:[0,1]
	v_pk_mul_f32 v[140:141], v[14:15], v[140:141] op_sel_hi:[0,1]
	v_pk_mul_f32 v[142:143], v[14:15], v[142:143] op_sel_hi:[0,1]
	v_pk_mul_f32 v[128:129], v[16:17], v[128:129]
	v_pk_mul_f32 v[130:131], v[18:19], v[130:131]
	v_pk_mul_f32 v[132:133], v[20:21], v[132:133]
	v_pk_mul_f32 v[134:135], v[22:23], v[134:135]
	v_pk_mul_f32 v[136:137], v[24:25], v[136:137]
	v_pk_mul_f32 v[138:139], v[26:27], v[138:139]
	v_pk_mul_f32 v[140:141], v[28:29], v[140:141]
	v_pk_mul_f32 v[142:143], v[30:31], v[142:143]
	global_store_dwordx4 v[252:253], v[128:131], off
	global_store_dwordx4 v[252:253], v[132:135], off offset:16
	global_store_dwordx4 v[252:253], v[136:139], off offset:2048
	global_store_dwordx4 v[252:253], v[140:143], off offset:2064
	v_lshl_add_u64 v[252:253], v[252:253], 0, s[16:17]
	s_waitcnt vmcnt(32)
	v_add_f32_e32 v4, v176, v177
	v_add_f32_e32 v5, v178, v179
	v_add_f32_e32 v4, v4, v5
	v_add_f32_e32 v5, v180, v181
	v_add_f32_e32 v6, v182, v183
	v_add_f32_e32 v5, v5, v6
	v_add_f32_e32 v4, v4, v5
	v_add_f32_e32 v5, v184, v185
	v_add_f32_e32 v6, v186, v187
	v_add_f32_e32 v5, v5, v6
	v_add_f32_e32 v4, v4, v5
	v_add_f32_e32 v5, v188, v189
	v_add_f32_e32 v6, v190, v191
	v_add_f32_e32 v5, v5, v6
	v_add_f32_e32 v4, v4, v5
	v_mov_b32_e32 v5, 0x358637bd
	v_fmamk_f32 v4, v4, 0x3a800000, v5
	v_rsq_f32_e32 v14, v4
	v_lshlrev_b32_e32 v176, 16, v192
	v_and_b32_e32 v177, 0xffff0000, v192
	v_lshlrev_b32_e32 v178, 16, v193
	v_and_b32_e32 v179, 0xffff0000, v193
	v_lshlrev_b32_e32 v180, 16, v194
	v_and_b32_e32 v181, 0xffff0000, v194
	v_lshlrev_b32_e32 v182, 16, v195
	v_and_b32_e32 v183, 0xffff0000, v195
	v_lshlrev_b32_e32 v184, 16, v196
	v_and_b32_e32 v185, 0xffff0000, v196
	v_lshlrev_b32_e32 v186, 16, v197
	v_and_b32_e32 v187, 0xffff0000, v197
	v_lshlrev_b32_e32 v188, 16, v198
	v_and_b32_e32 v189, 0xffff0000, v198
	v_lshlrev_b32_e32 v190, 16, v199
	v_and_b32_e32 v191, 0xffff0000, v199
	v_pk_mul_f32 v[176:177], v[14:15], v[176:177] op_sel_hi:[0,1]
	v_pk_mul_f32 v[178:179], v[14:15], v[178:179] op_sel_hi:[0,1]
	v_pk_mul_f32 v[180:181], v[14:15], v[180:181] op_sel_hi:[0,1]
	v_pk_mul_f32 v[182:183], v[14:15], v[182:183] op_sel_hi:[0,1]
	v_pk_mul_f32 v[184:185], v[14:15], v[184:185] op_sel_hi:[0,1]
	v_pk_mul_f32 v[186:187], v[14:15], v[186:187] op_sel_hi:[0,1]
	v_pk_mul_f32 v[188:189], v[14:15], v[188:189] op_sel_hi:[0,1]
	v_pk_mul_f32 v[190:191], v[14:15], v[190:191] op_sel_hi:[0,1]
	v_pk_mul_f32 v[176:177], v[16:17], v[176:177]
	v_pk_mul_f32 v[178:179], v[18:19], v[178:179]
	v_pk_mul_f32 v[180:181], v[20:21], v[180:181]
	v_pk_mul_f32 v[182:183], v[22:23], v[182:183]
	v_pk_mul_f32 v[184:185], v[24:25], v[184:185]
	v_pk_mul_f32 v[186:187], v[26:27], v[186:187]
	v_pk_mul_f32 v[188:189], v[28:29], v[188:189]
	v_pk_mul_f32 v[190:191], v[30:31], v[190:191]
	global_store_dwordx4 v[252:253], v[176:179], off
	global_store_dwordx4 v[252:253], v[180:183], off offset:16
	global_store_dwordx4 v[252:253], v[184:187], off offset:2048
	global_store_dwordx4 v[252:253], v[188:191], off offset:2064
	v_lshl_add_u64 v[252:253], v[252:253], 0, s[16:17]
	s_waitcnt vmcnt(30)
	v_add_f32_e32 v4, v200, v201
	v_add_f32_e32 v5, v202, v203
	v_add_f32_e32 v4, v4, v5
	v_add_f32_e32 v5, v204, v205
	v_add_f32_e32 v6, v206, v207
	v_add_f32_e32 v5, v5, v6
	v_add_f32_e32 v4, v4, v5
	v_add_f32_e32 v5, v208, v209
	v_add_f32_e32 v6, v210, v211
	v_add_f32_e32 v5, v5, v6
	v_add_f32_e32 v4, v4, v5
	v_add_f32_e32 v5, v212, v213
	v_add_f32_e32 v6, v214, v215
	v_add_f32_e32 v5, v5, v6
	v_add_f32_e32 v4, v4, v5
	v_mov_b32_e32 v5, 0x358637bd
	v_fmamk_f32 v4, v4, 0x3a800000, v5
	v_rsq_f32_e32 v14, v4
	v_lshlrev_b32_e32 v200, 16, v216
	v_and_b32_e32 v201, 0xffff0000, v216
	v_lshlrev_b32_e32 v202, 16, v217
	v_and_b32_e32 v203, 0xffff0000, v217
	v_lshlrev_b32_e32 v204, 16, v218
	v_and_b32_e32 v205, 0xffff0000, v218
	v_lshlrev_b32_e32 v206, 16, v219
	v_and_b32_e32 v207, 0xffff0000, v219
	v_lshlrev_b32_e32 v208, 16, v220
	v_and_b32_e32 v209, 0xffff0000, v220
	v_lshlrev_b32_e32 v210, 16, v221
	v_and_b32_e32 v211, 0xffff0000, v221
	v_lshlrev_b32_e32 v212, 16, v222
	v_and_b32_e32 v213, 0xffff0000, v222
	v_lshlrev_b32_e32 v214, 16, v223
	v_and_b32_e32 v215, 0xffff0000, v223
	v_pk_mul_f32 v[200:201], v[14:15], v[200:201] op_sel_hi:[0,1]
	v_pk_mul_f32 v[202:203], v[14:15], v[202:203] op_sel_hi:[0,1]
	v_pk_mul_f32 v[204:205], v[14:15], v[204:205] op_sel_hi:[0,1]
	v_pk_mul_f32 v[206:207], v[14:15], v[206:207] op_sel_hi:[0,1]
	v_pk_mul_f32 v[208:209], v[14:15], v[208:209] op_sel_hi:[0,1]
	v_pk_mul_f32 v[210:211], v[14:15], v[210:211] op_sel_hi:[0,1]
	v_pk_mul_f32 v[212:213], v[14:15], v[212:213] op_sel_hi:[0,1]
	v_pk_mul_f32 v[214:215], v[14:15], v[214:215] op_sel_hi:[0,1]
	v_pk_mul_f32 v[200:201], v[16:17], v[200:201]
	v_pk_mul_f32 v[202:203], v[18:19], v[202:203]
	v_pk_mul_f32 v[204:205], v[20:21], v[204:205]
	v_pk_mul_f32 v[206:207], v[22:23], v[206:207]
	v_pk_mul_f32 v[208:209], v[24:25], v[208:209]
	v_pk_mul_f32 v[210:211], v[26:27], v[210:211]
	v_pk_mul_f32 v[212:213], v[28:29], v[212:213]
	v_pk_mul_f32 v[214:215], v[30:31], v[214:215]
	global_store_dwordx4 v[252:253], v[200:203], off
	global_store_dwordx4 v[252:253], v[204:207], off offset:16
	global_store_dwordx4 v[252:253], v[208:211], off offset:2048
	global_store_dwordx4 v[252:253], v[212:215], off offset:2064
	v_lshl_add_u64 v[252:253], v[252:253], 0, s[16:17]
	s_waitcnt vmcnt(28)
	v_add_f32_e32 v4, v224, v225
	v_add_f32_e32 v5, v226, v227
	v_add_f32_e32 v4, v4, v5
	v_add_f32_e32 v5, v228, v229
	v_add_f32_e32 v6, v230, v231
	v_add_f32_e32 v5, v5, v6
	v_add_f32_e32 v4, v4, v5
	v_add_f32_e32 v5, v232, v233
	v_add_f32_e32 v6, v234, v235
	v_add_f32_e32 v5, v5, v6
	v_add_f32_e32 v4, v4, v5
	v_add_f32_e32 v5, v236, v237
	v_add_f32_e32 v6, v238, v239
	v_add_f32_e32 v5, v5, v6
	v_add_f32_e32 v4, v4, v5
	v_mov_b32_e32 v5, 0x358637bd
	v_fmamk_f32 v4, v4, 0x3a800000, v5
	v_rsq_f32_e32 v14, v4
	v_lshlrev_b32_e32 v224, 16, v240
	v_and_b32_e32 v225, 0xffff0000, v240
	v_lshlrev_b32_e32 v226, 16, v241
	v_and_b32_e32 v227, 0xffff0000, v241
	v_lshlrev_b32_e32 v228, 16, v242
	v_and_b32_e32 v229, 0xffff0000, v242
	v_lshlrev_b32_e32 v230, 16, v243
	v_and_b32_e32 v231, 0xffff0000, v243
	v_lshlrev_b32_e32 v232, 16, v244
	v_and_b32_e32 v233, 0xffff0000, v244
	v_lshlrev_b32_e32 v234, 16, v245
	v_and_b32_e32 v235, 0xffff0000, v245
	v_lshlrev_b32_e32 v236, 16, v246
	v_and_b32_e32 v237, 0xffff0000, v246
	v_lshlrev_b32_e32 v238, 16, v247
	v_and_b32_e32 v239, 0xffff0000, v247
	v_pk_mul_f32 v[224:225], v[14:15], v[224:225] op_sel_hi:[0,1]
	v_pk_mul_f32 v[226:227], v[14:15], v[226:227] op_sel_hi:[0,1]
	v_pk_mul_f32 v[228:229], v[14:15], v[228:229] op_sel_hi:[0,1]
	v_pk_mul_f32 v[230:231], v[14:15], v[230:231] op_sel_hi:[0,1]
	v_pk_mul_f32 v[232:233], v[14:15], v[232:233] op_sel_hi:[0,1]
	v_pk_mul_f32 v[234:235], v[14:15], v[234:235] op_sel_hi:[0,1]
	v_pk_mul_f32 v[236:237], v[14:15], v[236:237] op_sel_hi:[0,1]
	v_pk_mul_f32 v[238:239], v[14:15], v[238:239] op_sel_hi:[0,1]
	v_pk_mul_f32 v[224:225], v[16:17], v[224:225]
	v_pk_mul_f32 v[226:227], v[18:19], v[226:227]
	v_pk_mul_f32 v[228:229], v[20:21], v[228:229]
	v_pk_mul_f32 v[230:231], v[22:23], v[230:231]
	v_pk_mul_f32 v[232:233], v[24:25], v[232:233]
	v_pk_mul_f32 v[234:235], v[26:27], v[234:235]
	v_pk_mul_f32 v[236:237], v[28:29], v[236:237]
	v_pk_mul_f32 v[238:239], v[30:31], v[238:239]
	global_store_dwordx4 v[252:253], v[224:227], off
	global_store_dwordx4 v[252:253], v[228:231], off offset:16
	global_store_dwordx4 v[252:253], v[232:235], off offset:2048
	global_store_dwordx4 v[252:253], v[236:239], off offset:2064
	s_branch .LBB0_1716
.Lfin_orig:
	s_load_dwordx2 s[10:11], s[66:67], 0x28
	s_waitcnt lgkmcnt(0)
	s_add_u32 s2, s6, 0xd400000
	v_lshlrev_b32_e32 v1, 3, v1
	s_addc_u32 s3, s7, 0
	v_and_b32_e32 v2, 0x1f8, v1
	s_add_u32 s8, s6, 0xb400000
	v_mov_b32_e32 v5, 0
	v_lshlrev_b32_e32 v4, 2, v2
	s_addc_u32 s9, s7, 0
	v_lshl_add_u64 v[4:5], s[10:11], 0, v[4:5]
	v_or_b32_e32 v6, 0x200, v2
	s_mov_b64 s[10:11], 0
	v_mov_b32_e32 v3, 0x358637bd
	s_mov_b32 s12, 0x800000
	s_movk_i32 s13, 0x3fff
